# phase-0 weight conversion tile loop hand-written: LDS-DMA ring 3 tiles in flight, 1 barrier per tile, conflict-free rotated image
# baseline (speedup 1.0000x reference)
; #define PREF const __attribute__((address_space(4))) Params&
; __device__ __forceinline__ int tid_opaque() { int t = threadIdx.x; asm volatile("" : "+v"(t)); return t; }
; __device__ __forceinline__ TileJob tile_job(PREF P, int gt) {
;     const int l = gt / TILES_PER_LAYER, tt = gt - l * TILES_PER_LAYER; unsigned char* wl = P.ws + l * SZ_LAYER; TileJob J; int kt, nt;
;     if (tt < 3584) { J.src = P.w_in + (size_t)l * DM * INW; J.dst = (bf16_t*)(wl + LO_WIN); J.K = DM; J.N = INW; kt = tt & 15; nt = tt >> 4; J.drow0 = nt * 64; }
;     else if (tt < 3584 + 768) { const int e = tt - 3584, w = e >> 8, f = e & 255; J.src = (w == 0 ? P.proj_a : (w == 1 ? P.proj_b : P.proj_c)) + (size_t)l * 1024 * DM;
;         J.dst = (bf16_t*)(wl + LO_PA + (size_t)w * SZ_P); J.K = 1024; J.N = DM; kt = f & 7; nt = f >> 3; J.drow0 = nt * 64; }
;     else if (tt < 4352 + 256) { const int e = tt - 4352, w = e >> 7, f = e & 127; J.src = (w == 0 ? P.glu_wa : P.glu_wb) + (size_t)l * 1024 * 1024; J.dst = (bf16_t*)(wl + LO_GLU);
;         J.K = 1024; J.N = 1024; kt = f & 7; nt = f >> 3; const int n0 = nt * 64; J.drow0 = (n0 >> 7) * 256 + (n0 & 127) + w * 128; }
;     else if (tt < 4608 + 128) { const int f = tt - 4608; J.src = P.fourier_w + (size_t)l * 1024 * 1024; J.dst = (bf16_t*)(wl + LO_FW); J.K = 1024; J.N = 1024; kt = f & 7; nt = f >> 3; J.drow0 = nt * 64; }
;     else { const int f = tt - 4736; J.src = P.w_out + (size_t)l * DM * DM; J.dst = (bf16_t*)(wl + LO_WO); J.K = DM; J.N = DM; kt = f & 15; nt = f >> 4; J.drow0 = nt * 64; }
;     J.k0 = kt * 128; J.n0 = nt * 64; return J;
; __device__ __forceinline__ void phase_prep(PREF P, unsigned char* shm) {
;     ...
;     const int end = (start + cnt) < total ? (start + cnt) : total;
;     const int tid = tid_opaque(), lr = tid >> 4, lc = (tid & 15) * 4;
;     if (start < end) {
;         int cur = start; TileJob J = tile_job(P, cur); f32x4 v[4];
; #pragma unroll
;         for (int i = 0; i < 4; ++i) v[i] = *(const f32x4*)(J.src + (size_t)(J.k0 + lr + 32 * i) * J.N + J.n0 + lc);
.LBB0_219:
	s_add_i32 s0, s11, s0
	s_min_i32 s0, s0, 0x2900
	v_mov_b32_e32 v20, v0
	s_cmp_ge_i32 s11, s0
	s_cbranch_scc1 .LBB0_258
	s_load_dwordx2 s[12:13], s[6:7], 0xd0
	s_load_dwordx2 s[14:15], s[6:7], 0x40
	s_load_dwordx2 s[16:17], s[6:7], 0xa8
	s_load_dwordx2 s[18:19], s[6:7], 0xb0
	s_load_dwordx2 s[20:21], s[6:7], 0xb8
	s_load_dwordx2 s[22:23], s[6:7], 0x90
	s_load_dwordx2 s[24:25], s[6:7], 0x98
	s_load_dwordx2 s[26:27], s[6:7], 0xa0
	s_load_dwordx2 s[28:29], s[6:7], 0xc0
	v_and_b32_e32 v1, 63, v20
	v_lshrrev_b32_e32 v2, 6, v20
	s_nop 0
	v_readfirstlane_b32 s30, v2
	v_lshrrev_b32_e32 v2, 4, v1
	v_and_b32_e32 v3, 15, v1
	s_nop 3
	v_subrev_u32_e32 v3, s30, v3
	v_and_b32_e32 v3, 15, v3
	v_lshlrev_b32_e32 v3, 4, v3
	v_lshrrev_b32_e32 v4, 3, v20
	v_and_b32_e32 v5, 7, v20
	v_lshrrev_b32_e32 v6, 2, v4
	v_add_u32_e32 v6, v6, v5
	v_and_b32_e32 v6, 15, v6
	v_lshlrev_b32_e32 v6, 4, v6
	v_and_b32_e32 v9, 3, v4
	v_lshl_add_u32 v6, v9, 2, v6
	v_lshl_add_u32 v6, v5, 12, v6
	v_add_u32_e32 v6, 16, v6
	v_lshlrev_b32_e32 v5, 5, v5
	s_mov_b32 s31, 0
	s_waitcnt vmcnt(0) lgkmcnt(0)
	s_barrier
	s_add_u32 s9, s11, 0
	s_cmp_lt_u32 s9, s0
	s_cbranch_scc0 .Lp0_pro_done
	s_cmpk_ge_u32 s9, 0x1480
	s_cselect_b32 s51, 1, 0
	s_mul_i32 s52, s51, 0x1480
	s_sub_u32 s52, s9, s52
	s_mul_i32 s53, s51, 0x6e22000
	s_add_u32 s40, s12, s53
	s_addc_u32 s41, s13, 0
	s_cmpk_lt_u32 s52, 0xe00
	s_cbranch_scc1 .Lp0j_win_p0
	s_cmpk_lt_u32 s52, 0x1100
	s_cbranch_scc1 .Lp0j_proj_p0
	s_cmpk_lt_u32 s52, 0x1200
	s_cbranch_scc1 .Lp0j_glu_p0
	s_cmpk_lt_u32 s52, 0x1280
	s_cbranch_scc1 .Lp0j_fw_p0
	s_sub_u32 s52, s52, 0x1280
	s_and_b32 s54, s52, 15
	s_lshr_b32 s55, s52, 4
	s_lshl_b32 s56, s51, 24
	s_add_u32 s32, s28, s56
	s_addc_u32 s33, s29, 0
	s_movk_i32 s57, 0x800
	s_movk_i32 s58, 0x800
	s_mov_b32 s59, 0x4e00000
	s_lshl_b32 s60, s55, 6
	s_branch .Lp0j_tail_p0
.Lp0j_win_p0:
	s_and_b32 s54, s52, 15
	s_lshr_b32 s55, s52, 4
	s_mul_i32 s56, s51, 0x7000000
	s_add_u32 s32, s14, s56
	s_addc_u32 s33, s15, 0
	s_movk_i32 s57, 0x3800
	s_movk_i32 s58, 0x800
	s_mov_b32 s59, 0
	s_lshl_b32 s60, s55, 6
	s_branch .Lp0j_tail_p0
.Lp0j_proj_p0:
	s_sub_u32 s52, s52, 0xe00
	s_lshr_b32 s61, s52, 8
	s_and_b32 s52, s52, 0xff
	s_and_b32 s54, s52, 7
	s_lshr_b32 s55, s52, 3
	s_cmp_eq_u32 s61, 0
	s_cselect_b32 s62, s16, s18
	s_cselect_b32 s63, s17, s19
	s_cmp_eq_u32 s61, 2
	s_cselect_b32 s62, s20, s62
	s_cselect_b32 s63, s21, s63
	s_lshl_b32 s56, s51, 23
	s_add_u32 s32, s62, s56
	s_addc_u32 s33, s63, 0
	s_movk_i32 s57, 0x800
	s_movk_i32 s58, 0x400
	s_lshl_b32 s59, s61, 22
	s_add_u32 s59, s59, 0x3800000
	s_lshl_b32 s60, s55, 6
	s_branch .Lp0j_tail_p0
.Lp0j_glu_p0:
	s_sub_u32 s52, s52, 0x1100
	s_lshr_b32 s61, s52, 7
	s_and_b32 s52, s52, 0x7f
	s_and_b32 s54, s52, 7
	s_lshr_b32 s55, s52, 3
	s_cmp_eq_u32 s61, 0
	s_cselect_b32 s62, s22, s24
	s_cselect_b32 s63, s23, s25
	s_lshl_b32 s56, s51, 22
	s_add_u32 s32, s62, s56
	s_addc_u32 s33, s63, 0
	s_movk_i32 s57, 0x400
	s_movk_i32 s58, 0x400
	s_mov_b32 s59, 0x4400000
	s_lshl_b32 s60, s55, 6
	s_lshr_b32 s67, s60, 7
	s_lshl_b32 s67, s67, 8
	s_and_b32 s60, s60, 0x7f
	s_add_u32 s60, s60, s67
	s_lshl_b32 s67, s61, 7
	s_add_u32 s60, s60, s67
	s_branch .Lp0j_tail_p0
.Lp0j_fw_p0:
	s_sub_u32 s52, s52, 0x1200
	s_and_b32 s54, s52, 7
	s_lshr_b32 s55, s52, 3
	s_lshl_b32 s56, s51, 22
	s_add_u32 s32, s26, s56
	s_addc_u32 s33, s27, 0
	s_movk_i32 s57, 0x400
	s_movk_i32 s58, 0x400
	s_mov_b32 s59, 0x4800000
	s_lshl_b32 s60, s55, 6
.Lp0j_tail_p0:
	s_lshl_b32 s54, s54, 7
	s_lshl_b32 s55, s55, 6
	s_mul_i32 s56, s54, s57
	s_add_u32 s56, s56, s55
	s_lshl_b32 s56, s56, 2
	s_add_u32 s32, s32, s56
	s_addc_u32 s33, s33, 0
	s_lshl_b32 s34, s57, 2
	s_mul_i32 s56, s60, s58
	s_add_u32 s56, s56, s54
	s_lshl_b32 s56, s56, 1
	s_add_u32 s56, s56, s59
	s_add_u32 s40, s40, s56
	s_addc_u32 s41, s41, 0
	s_lshl_b32 s42, s58, 1
	s_and_b32 s10, s9, 3
	v_mad_u32_u24 v7, v2, s34, v3
	s_mul_i32 s1, s30, s34
	s_lshl_b32 s1, s1, 4
	s_add_u32 s2, s32, s1
	s_addc_u32 s3, s33, 0
	s_lshl_b32 s4, s34, 2
	s_lshl_b32 s5, s10, 15
	s_lshl_b32 s8, s30, 12
	s_add_u32 s5, s5, s8
	s_add_u32 s5, s5, 16
	s_mov_b32 m0, s5
	s_nop 0
	global_load_lds_dwordx4 v7, s[2:3]
	s_add_u32 s2, s2, s4
	s_addc_u32 s3, s3, 0
	s_add_u32 s5, s5, 0x400
	s_mov_b32 m0, s5
	s_nop 0
	global_load_lds_dwordx4 v7, s[2:3]
	s_add_u32 s2, s2, s4
	s_addc_u32 s3, s3, 0
	s_add_u32 s5, s5, 0x400
	s_mov_b32 m0, s5
	s_nop 0
	global_load_lds_dwordx4 v7, s[2:3]
	s_add_u32 s2, s2, s4
	s_addc_u32 s3, s3, 0
	s_add_u32 s5, s5, 0x400
	s_mov_b32 m0, s5
	s_nop 0
	global_load_lds_dwordx4 v7, s[2:3]
	s_add_u32 s9, s11, 1
	s_cmp_lt_u32 s9, s0
	s_cbranch_scc0 .Lp0_pro_done
	s_cmpk_ge_u32 s9, 0x1480
	s_cselect_b32 s51, 1, 0
	s_mul_i32 s52, s51, 0x1480
	s_sub_u32 s52, s9, s52
	s_mul_i32 s53, s51, 0x6e22000
	s_add_u32 s44, s12, s53
	s_addc_u32 s45, s13, 0
	s_cmpk_lt_u32 s52, 0xe00
	s_cbranch_scc1 .Lp0j_win_p1
	s_cmpk_lt_u32 s52, 0x1100
	s_cbranch_scc1 .Lp0j_proj_p1
	s_cmpk_lt_u32 s52, 0x1200
	s_cbranch_scc1 .Lp0j_glu_p1
	s_cmpk_lt_u32 s52, 0x1280
	s_cbranch_scc1 .Lp0j_fw_p1
	s_sub_u32 s52, s52, 0x1280
	s_and_b32 s54, s52, 15
	s_lshr_b32 s55, s52, 4
	s_lshl_b32 s56, s51, 24
	s_add_u32 s32, s28, s56
	s_addc_u32 s33, s29, 0
	s_movk_i32 s57, 0x800
	s_movk_i32 s58, 0x800
	s_mov_b32 s59, 0x4e00000
	s_lshl_b32 s60, s55, 6
	s_branch .Lp0j_tail_p1

; #define PREF const __attribute__((address_space(4))) Params&
; __device__ __forceinline__ TileJob tile_job(PREF P, int gt) {
;     const int l = gt / TILES_PER_LAYER, tt = gt - l * TILES_PER_LAYER; unsigned char* wl = P.ws + l * SZ_LAYER; TileJob J; int kt, nt;
;     if (tt < 3584) { J.src = P.w_in + (size_t)l * DM * INW; J.dst = (bf16_t*)(wl + LO_WIN); J.K = DM; J.N = INW; kt = tt & 15; nt = tt >> 4; J.drow0 = nt * 64; }
;     else if (tt < 3584 + 768) { const int e = tt - 3584, w = e >> 8, f = e & 255; J.src = (w == 0 ? P.proj_a : (w == 1 ? P.proj_b : P.proj_c)) + (size_t)l * 1024 * DM;
;         J.dst = (bf16_t*)(wl + LO_PA + (size_t)w * SZ_P); J.K = 1024; J.N = DM; kt = f & 7; nt = f >> 3; J.drow0 = nt * 64; }
;     else if (tt < 4352 + 256) { const int e = tt - 4352, w = e >> 7, f = e & 127; J.src = (w == 0 ? P.glu_wa : P.glu_wb) + (size_t)l * 1024 * 1024; J.dst = (bf16_t*)(wl + LO_GLU);
;         J.K = 1024; J.N = 1024; kt = f & 7; nt = f >> 3; const int n0 = nt * 64; J.drow0 = (n0 >> 7) * 256 + (n0 & 127) + w * 128; }
;     else if (tt < 4608 + 128) { const int f = tt - 4608; J.src = P.fourier_w + (size_t)l * 1024 * 1024; J.dst = (bf16_t*)(wl + LO_FW); J.K = 1024; J.N = 1024; kt = f & 7; nt = f >> 3; J.drow0 = nt * 64; }
;     else { const int f = tt - 4736; J.src = P.w_out + (size_t)l * DM * DM; J.dst = (bf16_t*)(wl + LO_WO); J.K = DM; J.N = DM; kt = f & 15; nt = f >> 4; J.drow0 = nt * 64; }
;     J.k0 = kt * 128; J.n0 = nt * 64; return J;
; __device__ __forceinline__ void phase_prep(PREF P, unsigned char* shm) {
;     ...
;         int cur = start; TileJob J = tile_job(P, cur); f32x4 v[4];
; #pragma unroll
;         for (int i = 0; i < 4; ++i) v[i] = *(const f32x4*)(J.src + (size_t)(J.k0 + lr + 32 * i) * J.N + J.n0 + lc);
.Lp0j_tail_p1:
	s_lshl_b32 s54, s54, 7
	s_lshl_b32 s55, s55, 6
	s_mul_i32 s56, s54, s57
	s_add_u32 s56, s56, s55
	s_lshl_b32 s56, s56, 2
	s_add_u32 s32, s32, s56
	s_addc_u32 s33, s33, 0
	s_lshl_b32 s34, s57, 2
	s_mul_i32 s56, s60, s58
	s_add_u32 s56, s56, s54
	s_lshl_b32 s56, s56, 1
	s_add_u32 s56, s56, s59
	s_add_u32 s44, s44, s56
	s_addc_u32 s45, s45, 0
	s_lshl_b32 s46, s58, 1
	s_and_b32 s10, s9, 3
	v_mad_u32_u24 v7, v2, s34, v3
	s_mul_i32 s1, s30, s34
	s_lshl_b32 s1, s1, 4
	s_add_u32 s2, s32, s1
	s_addc_u32 s3, s33, 0
	s_lshl_b32 s4, s34, 2
	s_lshl_b32 s5, s10, 15
	s_lshl_b32 s8, s30, 12
	s_add_u32 s5, s5, s8
	s_add_u32 s5, s5, 16
	s_mov_b32 m0, s5
	s_nop 0
	global_load_lds_dwordx4 v7, s[2:3]
	s_add_u32 s2, s2, s4
	s_addc_u32 s3, s3, 0
	s_add_u32 s5, s5, 0x400
	s_mov_b32 m0, s5
	s_nop 0
	global_load_lds_dwordx4 v7, s[2:3]
	s_add_u32 s2, s2, s4
	s_addc_u32 s3, s3, 0
	s_add_u32 s5, s5, 0x400
	s_mov_b32 m0, s5
	s_nop 0
	global_load_lds_dwordx4 v7, s[2:3]
	s_add_u32 s2, s2, s4
	s_addc_u32 s3, s3, 0
	s_add_u32 s5, s5, 0x400
	s_mov_b32 m0, s5
	s_nop 0
	global_load_lds_dwordx4 v7, s[2:3]
	s_add_u32 s9, s11, 2
	s_cmp_lt_u32 s9, s0
	s_cbranch_scc0 .Lp0_pro_done
	s_cmpk_ge_u32 s9, 0x1480
	s_cselect_b32 s51, 1, 0
	s_mul_i32 s52, s51, 0x1480
	s_sub_u32 s52, s9, s52
	s_mul_i32 s53, s51, 0x6e22000
	s_add_u32 s64, s12, s53
	s_addc_u32 s65, s13, 0
	s_cmpk_lt_u32 s52, 0xe00
	s_cbranch_scc1 .Lp0j_win_p2
	s_cmpk_lt_u32 s52, 0x1100
	s_cbranch_scc1 .Lp0j_proj_p2
	s_cmpk_lt_u32 s52, 0x1200
	s_cbranch_scc1 .Lp0j_glu_p2
	s_cmpk_lt_u32 s52, 0x1280
	s_cbranch_scc1 .Lp0j_fw_p2
	s_sub_u32 s52, s52, 0x1280
	s_and_b32 s54, s52, 15
	s_lshr_b32 s55, s52, 4
	s_lshl_b32 s56, s51, 24
	s_add_u32 s32, s28, s56
	s_addc_u32 s33, s29, 0
	s_movk_i32 s57, 0x800
	s_movk_i32 s58, 0x800
	s_mov_b32 s59, 0x4e00000
	s_lshl_b32 s60, s55, 6
	s_branch .Lp0j_tail_p2

; __device__ __forceinline__ void phase_prep(PREF P, unsigned char* shm) {
;     ...
;         int cur = start; TileJob J = tile_job(P, cur); f32x4 v[4];
; #pragma unroll
;         for (int i = 0; i < 4; ++i) v[i] = *(const f32x4*)(J.src + (size_t)(J.k0 + lr + 32 * i) * J.N + J.n0 + lc);
;         for (;;) {
; #pragma unroll
;             for (int i = 0; i < 4; ++i)
; #pragma unroll
;                 for (int j = 0; j < 4; ++j) sm[(lr + 32 * i) * 65 + lc + j] = v[i][j];
;             __syncthreads();
.Lp0j_tail_p2:
	s_lshl_b32 s54, s54, 7
	s_lshl_b32 s55, s55, 6
	s_mul_i32 s56, s54, s57
	s_add_u32 s56, s56, s55
	s_lshl_b32 s56, s56, 2
	s_add_u32 s32, s32, s56
	s_addc_u32 s33, s33, 0
	s_lshl_b32 s34, s57, 2
	s_mul_i32 s56, s60, s58
	s_add_u32 s56, s56, s54
	s_lshl_b32 s56, s56, 1
	s_add_u32 s56, s56, s59
	s_add_u32 s64, s64, s56
	s_addc_u32 s65, s65, 0
	s_lshl_b32 s66, s58, 1
	s_and_b32 s10, s9, 3
	v_mad_u32_u24 v7, v2, s34, v3
	s_mul_i32 s1, s30, s34
	s_lshl_b32 s1, s1, 4
	s_add_u32 s2, s32, s1
	s_addc_u32 s3, s33, 0
	s_lshl_b32 s4, s34, 2
	s_lshl_b32 s5, s10, 15
	s_lshl_b32 s8, s30, 12
	s_add_u32 s5, s5, s8
	s_add_u32 s5, s5, 16
	s_mov_b32 m0, s5
	s_nop 0
	global_load_lds_dwordx4 v7, s[2:3]
	s_add_u32 s2, s2, s4
	s_addc_u32 s3, s3, 0
	s_add_u32 s5, s5, 0x400
	s_mov_b32 m0, s5
	s_nop 0
	global_load_lds_dwordx4 v7, s[2:3]
	s_add_u32 s2, s2, s4
	s_addc_u32 s3, s3, 0
	s_add_u32 s5, s5, 0x400
	s_mov_b32 m0, s5
	s_nop 0
	global_load_lds_dwordx4 v7, s[2:3]
	s_add_u32 s2, s2, s4
	s_addc_u32 s3, s3, 0
	s_add_u32 s5, s5, 0x400
	s_mov_b32 m0, s5
	s_nop 0
	global_load_lds_dwordx4 v7, s[2:3]
.Lp0_pro_done:
.Lp0_tile:
	s_add_u32 s9, s11, 2
	s_cmp_lt_u32 s9, s0
	s_cbranch_scc0 .Lp0_w_tail
	s_cmp_ge_u32 s31, 3
	s_cbranch_scc0 .Lp0_w_head
	s_waitcnt vmcnt(14)
	s_branch .Lp0_w_done
.Lp0_w_head:
	s_waitcnt vmcnt(8)
	s_branch .Lp0_w_done

; __device__ __forceinline__ void phase_prep(PREF P, unsigned char* shm) {
;     ...
;             __syncthreads();
;             const TileJob C = J; const bool more = cur + 1 < end;
;             if (more) { J = tile_job(P, cur + 1);
; #pragma unroll
;                 for (int i = 0; i < 4; ++i) v[i] = *(const f32x4*)(J.src + (size_t)(J.k0 + lr + 32 * i) * J.N + J.n0 + lc); }
;             const int n = tid >> 3, kg = tid & 7;
; #pragma unroll
;             for (int h = 0; h < 2; ++h) { float f[8];
; #pragma unroll
;                 for (int j = 0; j < 8; ++j) f[j] = sm[(kg * 16 + h * 8 + j) * 65 + n];
.Lp0_w_done:
	s_barrier
	s_and_b32 s10, s11, 3
	s_lshl_b32 s10, s10, 15
	v_add_u32_e32 v9, s10, v6
	ds_read2st64_b32 v[10:11], v9 offset0:0 offset1:1
	ds_read2st64_b32 v[12:13], v9 offset0:2 offset1:3
	ds_read2st64_b32 v[14:15], v9 offset0:4 offset1:5
	ds_read2st64_b32 v[16:17], v9 offset0:6 offset1:7
	ds_read2st64_b32 v[18:19], v9 offset0:8 offset1:9
	ds_read2st64_b32 v[20:21], v9 offset0:10 offset1:11
	ds_read2st64_b32 v[22:23], v9 offset0:12 offset1:13
	ds_read2st64_b32 v[24:25], v9 offset0:14 offset1:15
	s_add_u32 s9, s11, 3
	s_cmp_lt_u32 s9, s0
	s_cbranch_scc0 .Lp0_no_dma
	s_cmpk_ge_u32 s9, 0x1480
	s_cselect_b32 s51, 1, 0
	s_mul_i32 s52, s51, 0x1480
	s_sub_u32 s52, s9, s52
	s_mul_i32 s53, s51, 0x6e22000
	s_add_u32 s36, s12, s53
	s_addc_u32 s37, s13, 0
	s_cmpk_lt_u32 s52, 0xe00
	s_cbranch_scc1 .Lp0j_win_l
	s_cmpk_lt_u32 s52, 0x1100
	s_cbranch_scc1 .Lp0j_proj_l
	s_cmpk_lt_u32 s52, 0x1200
	s_cbranch_scc1 .Lp0j_glu_l
	s_cmpk_lt_u32 s52, 0x1280
	s_cbranch_scc1 .Lp0j_fw_l
	s_sub_u32 s52, s52, 0x1280
	s_and_b32 s54, s52, 15
	s_lshr_b32 s55, s52, 4
	s_lshl_b32 s56, s51, 24
	s_add_u32 s32, s28, s56
	s_addc_u32 s33, s29, 0
	s_movk_i32 s57, 0x800
	s_movk_i32 s58, 0x800
	s_mov_b32 s59, 0x4e00000
	s_lshl_b32 s60, s55, 6
	s_branch .Lp0j_tail_l

; __device__ __forceinline__ u32x4 pack8(const float (&f)[8]) { u32x4 r; r[0] = cvt_pk_bf16(f[0], f[1]); r[1] = cvt_pk_bf16(f[2], f[3]); r[2] = cvt_pk_bf16(f[4], f[5]); r[3] = cvt_pk_bf16(f[6], f[7]); return r; }
; __device__ __forceinline__ void phase_prep(PREF P, unsigned char* shm) {
;     ...
;             if (more) { J = tile_job(P, cur + 1);
; #pragma unroll
;                 for (int i = 0; i < 4; ++i) v[i] = *(const f32x4*)(J.src + (size_t)(J.k0 + lr + 32 * i) * J.N + J.n0 + lc); }
;             const int n = tid >> 3, kg = tid & 7;
; #pragma unroll
;             for (int h = 0; h < 2; ++h) { float f[8];
; #pragma unroll
;                 for (int j = 0; j < 8; ++j) f[j] = sm[(kg * 16 + h * 8 + j) * 65 + n];
;                 *(u32x4*)(C.dst + (size_t)(C.drow0 + n) * C.K + C.k0 + kg * 16 + h * 8) = pack8(f); }
;             __syncthreads();
;             if (!more) break;
;             ++cur;
.Lp0j_tail_l:
	s_lshl_b32 s54, s54, 7
	s_lshl_b32 s55, s55, 6
	s_mul_i32 s56, s54, s57
	s_add_u32 s56, s56, s55
	s_lshl_b32 s56, s56, 2
	s_add_u32 s32, s32, s56
	s_addc_u32 s33, s33, 0
	s_lshl_b32 s34, s57, 2
	s_mul_i32 s56, s60, s58
	s_add_u32 s56, s56, s54
	s_lshl_b32 s56, s56, 1
	s_add_u32 s56, s56, s59
	s_add_u32 s36, s36, s56
	s_addc_u32 s37, s37, 0
	s_lshl_b32 s38, s58, 1
	s_and_b32 s10, s9, 3
	v_mad_u32_u24 v7, v2, s34, v3
	s_mul_i32 s1, s30, s34
	s_lshl_b32 s1, s1, 4
	s_add_u32 s2, s32, s1
	s_addc_u32 s3, s33, 0
	s_lshl_b32 s4, s34, 2
	s_lshl_b32 s5, s10, 15
	s_lshl_b32 s8, s30, 12
	s_add_u32 s5, s5, s8
	s_add_u32 s5, s5, 16
	s_mov_b32 m0, s5
	s_nop 0
	global_load_lds_dwordx4 v7, s[2:3]
	s_add_u32 s2, s2, s4
	s_addc_u32 s3, s3, 0
	s_add_u32 s5, s5, 0x400
	s_mov_b32 m0, s5
	s_nop 0
	global_load_lds_dwordx4 v7, s[2:3]
	s_add_u32 s2, s2, s4
	s_addc_u32 s3, s3, 0
	s_add_u32 s5, s5, 0x400
	s_mov_b32 m0, s5
	s_nop 0
	global_load_lds_dwordx4 v7, s[2:3]
	s_add_u32 s2, s2, s4
	s_addc_u32 s3, s3, 0
	s_add_u32 s5, s5, 0x400
	s_mov_b32 m0, s5
	s_nop 0
	global_load_lds_dwordx4 v7, s[2:3]
.Lp0_no_dma:
	v_mad_u32_u24 v8, v4, s42, v5
	s_waitcnt lgkmcnt(0)
	v_cvt_pk_bf16_f32 v26, v10, v11
	v_cvt_pk_bf16_f32 v27, v12, v13
	v_cvt_pk_bf16_f32 v28, v14, v15
	v_cvt_pk_bf16_f32 v29, v16, v17
	v_cvt_pk_bf16_f32 v30, v18, v19
	v_cvt_pk_bf16_f32 v31, v20, v21
	v_cvt_pk_bf16_f32 v32, v22, v23
	v_cvt_pk_bf16_f32 v33, v24, v25
	global_store_dwordx4 v8, v[26:29], s[40:41]
	global_store_dwordx4 v8, v[30:33], s[40:41] offset:16
	s_mov_b64 s[40:41], s[44:45]
	s_mov_b32 s42, s46
	s_mov_b64 s[44:45], s[64:65]
	s_mov_b32 s46, s66
	s_mov_b64 s[64:65], s[36:37]
	s_mov_b32 s66, s38
	s_add_u32 s11, s11, 1
	s_add_u32 s31, s31, 1
	s_cmp_lt_u32 s11, s0
	s_cbranch_scc1 .Lp0_tile
